# P0a w_mlp1/w_mlp2 transposes: item decode remapped so both 64-k halves of each 128-B output line come from adjacent waves of one workgroup
# speedup vs baseline: 1.0032x; 1.0032x over previous
.LBB0_12:
	s_cmpk_gt_i32 s4, 0x3c7f
	s_mov_b64 s[6:7], -1
	s_cbranch_scc0 .LBB0_77
	s_cmpk_gt_u32 s4, 0x427f
	s_cbranch_scc0 .LBB0_56
	s_cmpk_gt_u32 s4, 0x467f
	s_cbranch_scc0 .LBB0_35
	s_cmpk_gt_u32 s4, 0x667f
	s_cbranch_scc0 .LBB0_25
	s_cmpk_gt_u32 s4, 0xe67f
	s_cbranch_scc0 .LBB0_20
	s_add_i32 s62, s4, 0xffff1980
	s_load_dwordx2 s[8:9], s[12:13], 0xd0
	s_and_b32 s63, s62, 1
	s_lshl_b32 s63, s63, 7
	s_bfe_u32 s64, s62, 0x70001
	s_andn2_b32 s62, s62, 0xff
	s_or_b32 s62, s62, s63
	s_or_b32 s62, s62, s64
	s_lshr_b32 s6, s62, 1
	s_and_b32 s16, s6, 0x7fc0
	s_lshl_b32 s6, s62, 5
	s_and_b32 s6, s6, 0xfe0
	s_waitcnt lgkmcnt(0)
	s_lshl_b32 s10, s6, 2
	s_waitcnt lgkmcnt(0)
	s_add_u32 s8, s8, s10
	s_addc_u32 s9, s9, 0
	v_mov_b32_e32 v61, v35
	s_mov_b32 s7, 1
	v_lshl_add_u64 v[2:3], s[8:9], 0, v[60:61]
	v_or_b32_e32 v5, s16, v1
	v_or_b32_e32 v4, s16, v38
	s_mov_b32 s8, 0
	s_mov_b32 s9, 32

.LBB0_20:
	s_and_b64 vcc, exec, s[6:7]
	s_cbranch_vccz .LBB0_24
	s_load_dwordx2 s[8:9], s[12:13], 0xc8
	s_add_i32 s62, s4, 0xffff9980
	s_and_b32 s63, s62, 1
	s_lshl_b32 s63, s63, 9
	s_bfe_u32 s64, s62, 0x90001
	s_andn2_b32 s62, s62, 0x3ff
	s_or_b32 s62, s62, s63
	s_or_b32 s7, s62, s64
	s_lshr_b32 s6, s7, 3
	s_lshl_b32 s7, s7, 5
	s_and_b32 s7, s7, 0x3fe0
	s_and_b32 s6, s6, 0x1fc0
	s_waitcnt lgkmcnt(0)
	s_lshl_b32 s10, s7, 2
	s_waitcnt lgkmcnt(0)
	s_add_u32 s8, s8, s10
	s_addc_u32 s9, s9, 0
	v_mov_b32_e32 v61, v35
	v_lshl_add_u64 v[2:3], s[8:9], 0, v[60:61]
	v_or_b32_e32 v5, s6, v1
	v_or_b32_e32 v4, s6, v38
	s_mov_b32 s8, 1
	s_mov_b32 s9, 0
	s_mov_b32 s10, 32
